# EpiRes hand-written v2 with row reductions by v_permlane16/32_swap (no LDS round trips)
# speedup vs baseline: 1.0017x; 1.0017x over previous
; __device__ __forceinline__ u32x4 pack8(const f32x4 v0, const f32x4 v1) { u32x4 w; w.x = cvt_pk_bf16(v0[0], v0[1]); w.y = cvt_pk_bf16(v0[2], v0[3]); w.z = cvt_pk_bf16(v1[0], v1[1]); w.w = cvt_pk_bf16(v1[2], v1[3]); return w; }
; __device__ __forceinline__ float sumsq8(const f32x4 a, const f32x4 b) { return ((a[0] * a[0] + a[1] * a[1]) + (a[2] * a[2] + a[3] * a[3])) + ((b[0] * b[0] + b[1] * b[1]) + (b[2] * b[2] + b[3] * b[3])); }
; __device__ __forceinline__ void unpack8(const u32x4 w, f32x4& a, f32x4& b) { a = (f32x4){bf_lo(w.x), bf_hi(w.x), bf_lo(w.y), bf_hi(w.y)}; b = (f32x4){bf_lo(w.z), bf_hi(w.z), bf_lo(w.w), bf_hi(w.w)}; }
;     __device__ __forceinline__ void operator()(const f32x4 (&acc)[2][2][4][2], const Unit& u, int wr, int wc, int fr, int fq) const {
;         const int row0 = u.pm * BM + wr * 64 + fr, col0 = u.pn * BM + wc * 32 + 8 * fq;
;         u32x4 rv[8][2];
; #pragma unroll
;         for (int i = 0; i < 8; ++i)
; #pragma unroll
;             for (int bj = 0; bj < 2; ++bj) rv[i][bj] = *(const u32x4*)(Rin + (size_t)(row0 + (i >> 2) * HALF + (i & 3) * 16) * DMODEL + col0 + bj * HALF);
; #pragma unroll
;         for (int ai = 0; ai < 2; ++ai)
; #pragma unroll
;             for (int m = 0; m < 4; ++m) { const int row = row0 + ai * HALF + m * 16; float part = 0.f;
; #pragma unroll
;                 for (int bj = 0; bj < 2; ++bj) { f32x4 r0, r1; unpack8(rv[ai * 4 + m][bj], r0, r1);
;                     const f32x4 h0 = r0 + acc[ai][bj][m][0], h1 = r1 + acc[ai][bj][m][1]; part += sumsq8(h0, h1);
;                     *(u32x4*)(XBo + (size_t)row * DMODEL + col0 + bj * HALF) = pack8(h0, h1); }
;                 part += __shfl_xor(part, 16); part += __shfl_xor(part, 32);
;                 if (fq == 0) ssq[(size_t)row * 16 + u.pn * 4 + wc] = part; }
.LBB0_517:
	v_readfirstlane_b32 s0, v192
	v_and_b32_e32 v224, 15, v192
	s_bfe_u32 s17, s0, 0x20006
	s_lshr_b32 s0, s0, 8
	s_lshl_b32 s0, s0, 6
	s_lshl_b32 s1, s40, 8
	s_add_i32 s0, s0, s1
	v_add_u32_e32 v224, s0, v224
	v_bfe_u32 v225, v192, 4, 2
	s_lshl_b32 s0, s26, 8
	s_lshl_b32 s1, s17, 5
	s_or_b32 s0, s0, s1
	v_lshl_or_b32 v232, v225, 3, s0
	v_lshlrev_b32_e32 v226, 11, v224
	v_lshl_add_u32 v226, v232, 1, v226
	v_mov_b32_e32 v230, v226
	global_load_dwordx4 v[116:119], v230, s[6:7]
	global_load_dwordx4 v[120:123], v230, s[6:7] offset:256
	v_add_u32_e32 v230, 0x8000, v226
	global_load_dwordx4 v[128:131], v230, s[6:7]
	global_load_dwordx4 v[132:135], v230, s[6:7] offset:256
	v_add_u32_e32 v230, 0x10000, v226
	global_load_dwordx4 v[136:139], v230, s[6:7]
	global_load_dwordx4 v[140:143], v230, s[6:7] offset:256
	v_add_u32_e32 v230, 0x18000, v226
	global_load_dwordx4 v[144:147], v230, s[6:7]
	global_load_dwordx4 v[156:159], v230, s[6:7] offset:256
	v_add_u32_e32 v230, 0x40000, v226
	global_load_dwordx4 v[160:163], v230, s[6:7]
	global_load_dwordx4 v[164:167], v230, s[6:7] offset:256
	v_add_u32_e32 v230, 0x48000, v226
	global_load_dwordx4 v[168:171], v230, s[6:7]
	global_load_dwordx4 v[172:175], v230, s[6:7] offset:256
	v_add_u32_e32 v230, 0x50000, v226
	global_load_dwordx4 v[176:179], v230, s[6:7]
	global_load_dwordx4 v[180:183], v230, s[6:7] offset:256
	v_add_u32_e32 v230, 0x58000, v226
	global_load_dwordx4 v[184:187], v230, s[6:7]
	global_load_dwordx4 v[188:191], v230, s[6:7] offset:256
	v_lshlrev_b32_e32 v227, 6, v224
	s_lshl_b32 s26, s26, 2
	s_ashr_i32 s27, s26, 31
	s_lshl_b32 s72, s17, 2
	s_lshl_b32 s0, s26, 2
	s_add_i32 s0, s0, s72
	v_add_u32_e32 v227, s0, v227
	v_cmp_eq_u32_e32 vcc, 0, v225
	v_xor_b32_e32 v228, 16, v241
	v_xor_b32_e32 v229, 32, v241
	v_lshlrev_b32_e32 v228, 2, v228
	v_lshlrev_b32_e32 v229, 2, v229
	s_waitcnt vmcnt(14)
	v_lshlrev_b32_e32 v214, 16, v116
	v_and_b32_e32 v215, 0xffff0000, v116
	v_lshlrev_b32_e32 v216, 16, v117
	v_and_b32_e32 v217, 0xffff0000, v117
	v_add_f32_e32 v152, v152, v214
	v_add_f32_e32 v153, v153, v215
	v_add_f32_e32 v154, v154, v216
	v_add_f32_e32 v155, v155, v217
	v_mul_f32_e32 v218, v153, v153
	v_mul_f32_e32 v219, v155, v155
	v_fmac_f32_e32 v218, v152, v152
	v_fmac_f32_e32 v219, v154, v154
	v_add_f32_e32 v220, v218, v219
	v_lshlrev_b32_e32 v214, 16, v118
	v_and_b32_e32 v215, 0xffff0000, v118
	v_lshlrev_b32_e32 v216, 16, v119
	v_and_b32_e32 v217, 0xffff0000, v119
	v_add_f32_e32 v148, v148, v214
	v_add_f32_e32 v149, v149, v215
	v_add_f32_e32 v150, v150, v216
	v_add_f32_e32 v151, v151, v217
	v_mul_f32_e32 v218, v149, v149
	v_mul_f32_e32 v219, v151, v151
	v_fmac_f32_e32 v218, v148, v148
	v_fmac_f32_e32 v219, v150, v150
	v_add_f32_e32 v221, v218, v219
	v_cvt_pk_bf16_f32 v152, v152, v153
	v_cvt_pk_bf16_f32 v153, v154, v155
	v_cvt_pk_bf16_f32 v154, v148, v149
	v_cvt_pk_bf16_f32 v155, v150, v151
	v_mov_b32_e32 v230, v226
	global_store_dwordx4 v230, v[152:155], s[10:11]
	v_lshlrev_b32_e32 v214, 16, v120
	v_and_b32_e32 v215, 0xffff0000, v120
	v_lshlrev_b32_e32 v216, 16, v121
	v_and_b32_e32 v217, 0xffff0000, v121
	v_add_f32_e32 v124, v124, v214
	v_add_f32_e32 v125, v125, v215
	v_add_f32_e32 v126, v126, v216
	v_add_f32_e32 v127, v127, v217
	v_mul_f32_e32 v218, v125, v125
	v_mul_f32_e32 v219, v127, v127
	v_fmac_f32_e32 v218, v124, v124
	v_fmac_f32_e32 v219, v126, v126
	v_add_f32_e32 v222, v218, v219
	v_lshlrev_b32_e32 v214, 16, v122
	v_and_b32_e32 v215, 0xffff0000, v122
	v_lshlrev_b32_e32 v216, 16, v123
	v_and_b32_e32 v217, 0xffff0000, v123
	v_add_f32_e32 v112, v112, v214
	v_add_f32_e32 v113, v113, v215
	v_add_f32_e32 v114, v114, v216
	v_add_f32_e32 v115, v115, v217
	v_mul_f32_e32 v218, v113, v113
	v_mul_f32_e32 v219, v115, v115
	v_fmac_f32_e32 v218, v112, v112
	v_fmac_f32_e32 v219, v114, v114
	v_add_f32_e32 v223, v218, v219
	v_cvt_pk_bf16_f32 v124, v124, v125
	v_cvt_pk_bf16_f32 v125, v126, v127
	v_cvt_pk_bf16_f32 v126, v112, v113
	v_cvt_pk_bf16_f32 v127, v114, v115
	global_store_dwordx4 v230, v[124:127], s[10:11] offset:256
	v_add_f32_e32 v220, v220, v221
	v_add_f32_e32 v222, v222, v223
	v_add_f32_e32 v224, v220, v222
	v_mov_b32_e32 v231, v227
	v_mov_b32_e32 v225, v224
	s_nop 1
	v_permlane16_swap_b32_e32 v224, v225
	v_add_f32_e32 v224, v224, v225
	v_mov_b32_e32 v225, v224
	s_nop 1
	v_permlane32_swap_b32_e32 v224, v225
	v_add_f32_e32 v224, v224, v225
	s_and_saveexec_b64 s[0:1], vcc
	global_store_dword v231, v224, s[12:13]
	s_or_b64 exec, exec, s[0:1]
	s_waitcnt vmcnt(15)
; __device__ __forceinline__ u32x4 pack8(const f32x4 v0, const f32x4 v1) { u32x4 w; w.x = cvt_pk_bf16(v0[0], v0[1]); w.y = cvt_pk_bf16(v0[2], v0[3]); w.z = cvt_pk_bf16(v1[0], v1[1]); w.w = cvt_pk_bf16(v1[2], v1[3]); return w; }
; __device__ __forceinline__ float sumsq8(const f32x4 a, const f32x4 b) { return ((a[0] * a[0] + a[1] * a[1]) + (a[2] * a[2] + a[3] * a[3])) + ((b[0] * b[0] + b[1] * b[1]) + (b[2] * b[2] + b[3] * b[3])); }
; __device__ __forceinline__ void unpack8(const u32x4 w, f32x4& a, f32x4& b) { a = (f32x4){bf_lo(w.x), bf_hi(w.x), bf_lo(w.y), bf_hi(w.y)}; b = (f32x4){bf_lo(w.z), bf_hi(w.z), bf_lo(w.w), bf_hi(w.w)}; }
;     __device__ __forceinline__ void operator()(const f32x4 (&acc)[2][2][4][2], const Unit& u, int wr, int wc, int fr, int fq) const {
;     ...
; #pragma unroll
;         for (int ai = 0; ai < 2; ++ai)
; #pragma unroll
;             for (int m = 0; m < 4; ++m) { const int row = row0 + ai * HALF + m * 16; float part = 0.f;
; #pragma unroll
;                 for (int bj = 0; bj < 2; ++bj) { f32x4 r0, r1; unpack8(rv[ai * 4 + m][bj], r0, r1);
;                     const f32x4 h0 = r0 + acc[ai][bj][m][0], h1 = r1 + acc[ai][bj][m][1]; part += sumsq8(h0, h1);
;                     *(u32x4*)(XBo + (size_t)row * DMODEL + col0 + bj * HALF) = pack8(h0, h1); }
;                 part += __shfl_xor(part, 16); part += __shfl_xor(part, 32);
;                 if (fq == 0) ssq[(size_t)row * 16 + u.pn * 4 + wc] = part; }
	v_lshlrev_b32_e32 v214, 16, v128
	v_and_b32_e32 v215, 0xffff0000, v128
	v_lshlrev_b32_e32 v216, 16, v129
	v_and_b32_e32 v217, 0xffff0000, v129
	v_add_f32_e32 v108, v108, v214
	v_add_f32_e32 v109, v109, v215
	v_add_f32_e32 v110, v110, v216
	v_add_f32_e32 v111, v111, v217
	v_mul_f32_e32 v218, v109, v109
	v_mul_f32_e32 v219, v111, v111
	v_fmac_f32_e32 v218, v108, v108
	v_fmac_f32_e32 v219, v110, v110
	v_add_f32_e32 v220, v218, v219
	v_lshlrev_b32_e32 v214, 16, v130
	v_and_b32_e32 v215, 0xffff0000, v130
	v_lshlrev_b32_e32 v216, 16, v131
	v_and_b32_e32 v217, 0xffff0000, v131
	v_add_f32_e32 v104, v104, v214
	v_add_f32_e32 v105, v105, v215
	v_add_f32_e32 v106, v106, v216
	v_add_f32_e32 v107, v107, v217
	v_mul_f32_e32 v218, v105, v105
	v_mul_f32_e32 v219, v107, v107
	v_fmac_f32_e32 v218, v104, v104
	v_fmac_f32_e32 v219, v106, v106
	v_add_f32_e32 v221, v218, v219
	v_cvt_pk_bf16_f32 v108, v108, v109
	v_cvt_pk_bf16_f32 v109, v110, v111
	v_cvt_pk_bf16_f32 v110, v104, v105
	v_cvt_pk_bf16_f32 v111, v106, v107
	v_add_u32_e32 v230, 0x8000, v226
	global_store_dwordx4 v230, v[108:111], s[10:11]
	v_lshlrev_b32_e32 v214, 16, v132
	v_and_b32_e32 v215, 0xffff0000, v132
	v_lshlrev_b32_e32 v216, 16, v133
	v_and_b32_e32 v217, 0xffff0000, v133
	v_add_f32_e32 v100, v100, v214
	v_add_f32_e32 v101, v101, v215
	v_add_f32_e32 v102, v102, v216
	v_add_f32_e32 v103, v103, v217
	v_mul_f32_e32 v218, v101, v101
	v_mul_f32_e32 v219, v103, v103
	v_fmac_f32_e32 v218, v100, v100
	v_fmac_f32_e32 v219, v102, v102
	v_add_f32_e32 v222, v218, v219
	v_lshlrev_b32_e32 v214, 16, v134
	v_and_b32_e32 v215, 0xffff0000, v134
	v_lshlrev_b32_e32 v216, 16, v135
	v_and_b32_e32 v217, 0xffff0000, v135
	v_add_f32_e32 v96, v96, v214
	v_add_f32_e32 v97, v97, v215
	v_add_f32_e32 v98, v98, v216
	v_add_f32_e32 v99, v99, v217
	v_mul_f32_e32 v218, v97, v97
	v_mul_f32_e32 v219, v99, v99
	v_fmac_f32_e32 v218, v96, v96
	v_fmac_f32_e32 v219, v98, v98
	v_add_f32_e32 v223, v218, v219
	v_cvt_pk_bf16_f32 v100, v100, v101
	v_cvt_pk_bf16_f32 v101, v102, v103
	v_cvt_pk_bf16_f32 v102, v96, v97
	v_cvt_pk_bf16_f32 v103, v98, v99
	global_store_dwordx4 v230, v[100:103], s[10:11] offset:256
	v_add_f32_e32 v220, v220, v221
	v_add_f32_e32 v222, v222, v223
	v_add_f32_e32 v224, v220, v222
	v_add_u32_e32 v231, 0x400, v227
	v_mov_b32_e32 v225, v224
	s_nop 1
	v_permlane16_swap_b32_e32 v224, v225
	v_add_f32_e32 v224, v224, v225
	v_mov_b32_e32 v225, v224
	s_nop 1
	v_permlane32_swap_b32_e32 v224, v225
	v_add_f32_e32 v224, v224, v225
	s_and_saveexec_b64 s[0:1], vcc
	global_store_dword v231, v224, s[12:13]
	s_or_b64 exec, exec, s[0:1]
	s_waitcnt vmcnt(16)
	v_lshlrev_b32_e32 v214, 16, v136
	v_and_b32_e32 v215, 0xffff0000, v136
	v_lshlrev_b32_e32 v216, 16, v137
	v_and_b32_e32 v217, 0xffff0000, v137
	v_add_f32_e32 v92, v92, v214
	v_add_f32_e32 v93, v93, v215
	v_add_f32_e32 v94, v94, v216
	v_add_f32_e32 v95, v95, v217
	v_mul_f32_e32 v218, v93, v93
	v_mul_f32_e32 v219, v95, v95
	v_fmac_f32_e32 v218, v92, v92
	v_fmac_f32_e32 v219, v94, v94
	v_add_f32_e32 v220, v218, v219
	v_lshlrev_b32_e32 v214, 16, v138
	v_and_b32_e32 v215, 0xffff0000, v138
	v_lshlrev_b32_e32 v216, 16, v139
	v_and_b32_e32 v217, 0xffff0000, v139
	v_add_f32_e32 v88, v88, v214
	v_add_f32_e32 v89, v89, v215
	v_add_f32_e32 v90, v90, v216
	v_add_f32_e32 v91, v91, v217
	v_mul_f32_e32 v218, v89, v89
	v_mul_f32_e32 v219, v91, v91
	v_fmac_f32_e32 v218, v88, v88
	v_fmac_f32_e32 v219, v90, v90
	v_add_f32_e32 v221, v218, v219
	v_cvt_pk_bf16_f32 v92, v92, v93
	v_cvt_pk_bf16_f32 v93, v94, v95
	v_cvt_pk_bf16_f32 v94, v88, v89
	v_cvt_pk_bf16_f32 v95, v90, v91
	v_add_u32_e32 v230, 0x10000, v226
	global_store_dwordx4 v230, v[92:95], s[10:11]
	v_lshlrev_b32_e32 v214, 16, v140
	v_and_b32_e32 v215, 0xffff0000, v140
	v_lshlrev_b32_e32 v216, 16, v141
	v_and_b32_e32 v217, 0xffff0000, v141
	v_add_f32_e32 v84, v84, v214
	v_add_f32_e32 v85, v85, v215
	v_add_f32_e32 v86, v86, v216
	v_add_f32_e32 v87, v87, v217
	v_mul_f32_e32 v218, v85, v85
	v_mul_f32_e32 v219, v87, v87
	v_fmac_f32_e32 v218, v84, v84
	v_fmac_f32_e32 v219, v86, v86
	v_add_f32_e32 v222, v218, v219
	v_lshlrev_b32_e32 v214, 16, v142
	v_and_b32_e32 v215, 0xffff0000, v142
	v_lshlrev_b32_e32 v216, 16, v143
	v_and_b32_e32 v217, 0xffff0000, v143
	v_add_f32_e32 v80, v80, v214
	v_add_f32_e32 v81, v81, v215
	v_add_f32_e32 v82, v82, v216
	v_add_f32_e32 v83, v83, v217
	v_mul_f32_e32 v218, v81, v81
	v_mul_f32_e32 v219, v83, v83
	v_fmac_f32_e32 v218, v80, v80
	v_fmac_f32_e32 v219, v82, v82
	v_add_f32_e32 v223, v218, v219
	v_cvt_pk_bf16_f32 v84, v84, v85
	v_cvt_pk_bf16_f32 v85, v86, v87
	v_cvt_pk_bf16_f32 v86, v80, v81
	v_cvt_pk_bf16_f32 v87, v82, v83
	global_store_dwordx4 v230, v[84:87], s[10:11] offset:256
	v_add_f32_e32 v220, v220, v221
	v_add_f32_e32 v222, v222, v223
	v_add_f32_e32 v224, v220, v222
	v_add_u32_e32 v231, 0x800, v227
	v_mov_b32_e32 v225, v224
	s_nop 1
	v_permlane16_swap_b32_e32 v224, v225
	v_add_f32_e32 v224, v224, v225
	v_mov_b32_e32 v225, v224
	s_nop 1
	v_permlane32_swap_b32_e32 v224, v225
	v_add_f32_e32 v224, v224, v225
	s_and_saveexec_b64 s[0:1], vcc
	global_store_dword v231, v224, s[12:13]
	s_or_b64 exec, exec, s[0:1]
	s_waitcnt vmcnt(17)
; __device__ __forceinline__ u32x4 pack8(const f32x4 v0, const f32x4 v1) { u32x4 w; w.x = cvt_pk_bf16(v0[0], v0[1]); w.y = cvt_pk_bf16(v0[2], v0[3]); w.z = cvt_pk_bf16(v1[0], v1[1]); w.w = cvt_pk_bf16(v1[2], v1[3]); return w; }
; __device__ __forceinline__ float sumsq8(const f32x4 a, const f32x4 b) { return ((a[0] * a[0] + a[1] * a[1]) + (a[2] * a[2] + a[3] * a[3])) + ((b[0] * b[0] + b[1] * b[1]) + (b[2] * b[2] + b[3] * b[3])); }
; __device__ __forceinline__ void unpack8(const u32x4 w, f32x4& a, f32x4& b) { a = (f32x4){bf_lo(w.x), bf_hi(w.x), bf_lo(w.y), bf_hi(w.y)}; b = (f32x4){bf_lo(w.z), bf_hi(w.z), bf_lo(w.w), bf_hi(w.w)}; }
;     __device__ __forceinline__ void operator()(const f32x4 (&acc)[2][2][4][2], const Unit& u, int wr, int wc, int fr, int fq) const {
;     ...
; #pragma unroll
;         for (int ai = 0; ai < 2; ++ai)
; #pragma unroll
;             for (int m = 0; m < 4; ++m) { const int row = row0 + ai * HALF + m * 16; float part = 0.f;
; #pragma unroll
;                 for (int bj = 0; bj < 2; ++bj) { f32x4 r0, r1; unpack8(rv[ai * 4 + m][bj], r0, r1);
;                     const f32x4 h0 = r0 + acc[ai][bj][m][0], h1 = r1 + acc[ai][bj][m][1]; part += sumsq8(h0, h1);
;                     *(u32x4*)(XBo + (size_t)row * DMODEL + col0 + bj * HALF) = pack8(h0, h1); }
;                 part += __shfl_xor(part, 16); part += __shfl_xor(part, 32);
;                 if (fq == 0) ssq[(size_t)row * 16 + u.pn * 4 + wc] = part; }
	v_lshlrev_b32_e32 v214, 16, v144
	v_and_b32_e32 v215, 0xffff0000, v144
	v_lshlrev_b32_e32 v216, 16, v145
	v_and_b32_e32 v217, 0xffff0000, v145
	v_add_f32_e32 v76, v76, v214
	v_add_f32_e32 v77, v77, v215
	v_add_f32_e32 v78, v78, v216
	v_add_f32_e32 v79, v79, v217
	v_mul_f32_e32 v218, v77, v77
	v_mul_f32_e32 v219, v79, v79
	v_fmac_f32_e32 v218, v76, v76
	v_fmac_f32_e32 v219, v78, v78
	v_add_f32_e32 v220, v218, v219
	v_lshlrev_b32_e32 v214, 16, v146
	v_and_b32_e32 v215, 0xffff0000, v146
	v_lshlrev_b32_e32 v216, 16, v147
	v_and_b32_e32 v217, 0xffff0000, v147
	v_add_f32_e32 v72, v72, v214
	v_add_f32_e32 v73, v73, v215
	v_add_f32_e32 v74, v74, v216
	v_add_f32_e32 v75, v75, v217
	v_mul_f32_e32 v218, v73, v73
	v_mul_f32_e32 v219, v75, v75
	v_fmac_f32_e32 v218, v72, v72
	v_fmac_f32_e32 v219, v74, v74
	v_add_f32_e32 v221, v218, v219
	v_cvt_pk_bf16_f32 v76, v76, v77
	v_cvt_pk_bf16_f32 v77, v78, v79
	v_cvt_pk_bf16_f32 v78, v72, v73
	v_cvt_pk_bf16_f32 v79, v74, v75
	v_add_u32_e32 v230, 0x18000, v226
	global_store_dwordx4 v230, v[76:79], s[10:11]
	v_lshlrev_b32_e32 v214, 16, v156
	v_and_b32_e32 v215, 0xffff0000, v156
	v_lshlrev_b32_e32 v216, 16, v157
	v_and_b32_e32 v217, 0xffff0000, v157
	v_add_f32_e32 v68, v68, v214
	v_add_f32_e32 v69, v69, v215
	v_add_f32_e32 v70, v70, v216
	v_add_f32_e32 v71, v71, v217
	v_mul_f32_e32 v218, v69, v69
	v_mul_f32_e32 v219, v71, v71
	v_fmac_f32_e32 v218, v68, v68
	v_fmac_f32_e32 v219, v70, v70
	v_add_f32_e32 v222, v218, v219
	v_lshlrev_b32_e32 v214, 16, v158
	v_and_b32_e32 v215, 0xffff0000, v158
	v_lshlrev_b32_e32 v216, 16, v159
	v_and_b32_e32 v217, 0xffff0000, v159
	v_add_f32_e32 v64, v64, v214
	v_add_f32_e32 v65, v65, v215
	v_add_f32_e32 v66, v66, v216
	v_add_f32_e32 v67, v67, v217
	v_mul_f32_e32 v218, v65, v65
	v_mul_f32_e32 v219, v67, v67
	v_fmac_f32_e32 v218, v64, v64
	v_fmac_f32_e32 v219, v66, v66
	v_add_f32_e32 v223, v218, v219
	v_cvt_pk_bf16_f32 v68, v68, v69
	v_cvt_pk_bf16_f32 v69, v70, v71
	v_cvt_pk_bf16_f32 v70, v64, v65
	v_cvt_pk_bf16_f32 v71, v66, v67
	global_store_dwordx4 v230, v[68:71], s[10:11] offset:256
	v_add_f32_e32 v220, v220, v221
	v_add_f32_e32 v222, v222, v223
	v_add_f32_e32 v224, v220, v222
	v_add_u32_e32 v231, 0xc00, v227
	v_mov_b32_e32 v225, v224
	s_nop 1
	v_permlane16_swap_b32_e32 v224, v225
	v_add_f32_e32 v224, v224, v225
	v_mov_b32_e32 v225, v224
	s_nop 1
	v_permlane32_swap_b32_e32 v224, v225
	v_add_f32_e32 v224, v224, v225
	s_and_saveexec_b64 s[0:1], vcc
	global_store_dword v231, v224, s[12:13]
	s_or_b64 exec, exec, s[0:1]
	s_waitcnt vmcnt(18)
	v_lshlrev_b32_e32 v214, 16, v160
	v_and_b32_e32 v215, 0xffff0000, v160
	v_lshlrev_b32_e32 v216, 16, v161
	v_and_b32_e32 v217, 0xffff0000, v161
	v_add_f32_e32 v60, v60, v214
	v_add_f32_e32 v61, v61, v215
	v_add_f32_e32 v62, v62, v216
	v_add_f32_e32 v63, v63, v217
	v_mul_f32_e32 v218, v61, v61
	v_mul_f32_e32 v219, v63, v63
	v_fmac_f32_e32 v218, v60, v60
	v_fmac_f32_e32 v219, v62, v62
	v_add_f32_e32 v220, v218, v219
	v_lshlrev_b32_e32 v214, 16, v162
	v_and_b32_e32 v215, 0xffff0000, v162
	v_lshlrev_b32_e32 v216, 16, v163
	v_and_b32_e32 v217, 0xffff0000, v163
	v_add_f32_e32 v56, v56, v214
	v_add_f32_e32 v57, v57, v215
	v_add_f32_e32 v58, v58, v216
	v_add_f32_e32 v59, v59, v217
	v_mul_f32_e32 v218, v57, v57
	v_mul_f32_e32 v219, v59, v59
	v_fmac_f32_e32 v218, v56, v56
	v_fmac_f32_e32 v219, v58, v58
	v_add_f32_e32 v221, v218, v219
	v_cvt_pk_bf16_f32 v60, v60, v61
	v_cvt_pk_bf16_f32 v61, v62, v63
	v_cvt_pk_bf16_f32 v62, v56, v57
	v_cvt_pk_bf16_f32 v63, v58, v59
	v_add_u32_e32 v230, 0x40000, v226
	global_store_dwordx4 v230, v[60:63], s[10:11]
	v_lshlrev_b32_e32 v214, 16, v164
	v_and_b32_e32 v215, 0xffff0000, v164
	v_lshlrev_b32_e32 v216, 16, v165
	v_and_b32_e32 v217, 0xffff0000, v165
	v_add_f32_e32 v52, v52, v214
	v_add_f32_e32 v53, v53, v215
	v_add_f32_e32 v54, v54, v216
	v_add_f32_e32 v55, v55, v217
	v_mul_f32_e32 v218, v53, v53
	v_mul_f32_e32 v219, v55, v55
	v_fmac_f32_e32 v218, v52, v52
	v_fmac_f32_e32 v219, v54, v54
	v_add_f32_e32 v222, v218, v219
	v_lshlrev_b32_e32 v214, 16, v166
	v_and_b32_e32 v215, 0xffff0000, v166
	v_lshlrev_b32_e32 v216, 16, v167
	v_and_b32_e32 v217, 0xffff0000, v167
	v_add_f32_e32 v48, v48, v214
	v_add_f32_e32 v49, v49, v215
	v_add_f32_e32 v50, v50, v216
	v_add_f32_e32 v51, v51, v217
	v_mul_f32_e32 v218, v49, v49
	v_mul_f32_e32 v219, v51, v51
	v_fmac_f32_e32 v218, v48, v48
	v_fmac_f32_e32 v219, v50, v50
	v_add_f32_e32 v223, v218, v219
	v_cvt_pk_bf16_f32 v52, v52, v53
	v_cvt_pk_bf16_f32 v53, v54, v55
	v_cvt_pk_bf16_f32 v54, v48, v49
	v_cvt_pk_bf16_f32 v55, v50, v51
	global_store_dwordx4 v230, v[52:55], s[10:11] offset:256
	v_add_f32_e32 v220, v220, v221
	v_add_f32_e32 v222, v222, v223
	v_add_f32_e32 v224, v220, v222
	v_add_u32_e32 v231, 0x2000, v227
	v_mov_b32_e32 v225, v224
	s_nop 1
	v_permlane16_swap_b32_e32 v224, v225
	v_add_f32_e32 v224, v224, v225
	v_mov_b32_e32 v225, v224
	s_nop 1
	v_permlane32_swap_b32_e32 v224, v225
	v_add_f32_e32 v224, v224, v225
	s_and_saveexec_b64 s[0:1], vcc
	global_store_dword v231, v224, s[12:13]
	s_or_b64 exec, exec, s[0:1]
	s_waitcnt vmcnt(19)
; __device__ __forceinline__ u32x4 pack8(const f32x4 v0, const f32x4 v1) { u32x4 w; w.x = cvt_pk_bf16(v0[0], v0[1]); w.y = cvt_pk_bf16(v0[2], v0[3]); w.z = cvt_pk_bf16(v1[0], v1[1]); w.w = cvt_pk_bf16(v1[2], v1[3]); return w; }
; __device__ __forceinline__ float sumsq8(const f32x4 a, const f32x4 b) { return ((a[0] * a[0] + a[1] * a[1]) + (a[2] * a[2] + a[3] * a[3])) + ((b[0] * b[0] + b[1] * b[1]) + (b[2] * b[2] + b[3] * b[3])); }
; __device__ __forceinline__ void unpack8(const u32x4 w, f32x4& a, f32x4& b) { a = (f32x4){bf_lo(w.x), bf_hi(w.x), bf_lo(w.y), bf_hi(w.y)}; b = (f32x4){bf_lo(w.z), bf_hi(w.z), bf_lo(w.w), bf_hi(w.w)}; }
;     __device__ __forceinline__ void operator()(const f32x4 (&acc)[2][2][4][2], const Unit& u, int wr, int wc, int fr, int fq) const {
;     ...
; #pragma unroll
;         for (int ai = 0; ai < 2; ++ai)
; #pragma unroll
;             for (int m = 0; m < 4; ++m) { const int row = row0 + ai * HALF + m * 16; float part = 0.f;
; #pragma unroll
;                 for (int bj = 0; bj < 2; ++bj) { f32x4 r0, r1; unpack8(rv[ai * 4 + m][bj], r0, r1);
;                     const f32x4 h0 = r0 + acc[ai][bj][m][0], h1 = r1 + acc[ai][bj][m][1]; part += sumsq8(h0, h1);
;                     *(u32x4*)(XBo + (size_t)row * DMODEL + col0 + bj * HALF) = pack8(h0, h1); }
;                 part += __shfl_xor(part, 16); part += __shfl_xor(part, 32);
;                 if (fq == 0) ssq[(size_t)row * 16 + u.pn * 4 + wc] = part; }
	v_lshlrev_b32_e32 v214, 16, v168
	v_and_b32_e32 v215, 0xffff0000, v168
	v_lshlrev_b32_e32 v216, 16, v169
	v_and_b32_e32 v217, 0xffff0000, v169
	v_add_f32_e32 v44, v44, v214
	v_add_f32_e32 v45, v45, v215
	v_add_f32_e32 v46, v46, v216
	v_add_f32_e32 v47, v47, v217
	v_mul_f32_e32 v218, v45, v45
	v_mul_f32_e32 v219, v47, v47
	v_fmac_f32_e32 v218, v44, v44
	v_fmac_f32_e32 v219, v46, v46
	v_add_f32_e32 v220, v218, v219
	v_lshlrev_b32_e32 v214, 16, v170
	v_and_b32_e32 v215, 0xffff0000, v170
	v_lshlrev_b32_e32 v216, 16, v171
	v_and_b32_e32 v217, 0xffff0000, v171
	v_add_f32_e32 v40, v40, v214
	v_add_f32_e32 v41, v41, v215
	v_add_f32_e32 v42, v42, v216
	v_add_f32_e32 v43, v43, v217
	v_mul_f32_e32 v218, v41, v41
	v_mul_f32_e32 v219, v43, v43
	v_fmac_f32_e32 v218, v40, v40
	v_fmac_f32_e32 v219, v42, v42
	v_add_f32_e32 v221, v218, v219
	v_cvt_pk_bf16_f32 v44, v44, v45
	v_cvt_pk_bf16_f32 v45, v46, v47
	v_cvt_pk_bf16_f32 v46, v40, v41
	v_cvt_pk_bf16_f32 v47, v42, v43
	v_add_u32_e32 v230, 0x48000, v226
	global_store_dwordx4 v230, v[44:47], s[10:11]
	v_lshlrev_b32_e32 v214, 16, v172
	v_and_b32_e32 v215, 0xffff0000, v172
	v_lshlrev_b32_e32 v216, 16, v173
	v_and_b32_e32 v217, 0xffff0000, v173
	v_add_f32_e32 v36, v36, v214
	v_add_f32_e32 v37, v37, v215
	v_add_f32_e32 v38, v38, v216
	v_add_f32_e32 v39, v39, v217
	v_mul_f32_e32 v218, v37, v37
	v_mul_f32_e32 v219, v39, v39
	v_fmac_f32_e32 v218, v36, v36
	v_fmac_f32_e32 v219, v38, v38
	v_add_f32_e32 v222, v218, v219
	v_lshlrev_b32_e32 v214, 16, v174
	v_and_b32_e32 v215, 0xffff0000, v174
	v_lshlrev_b32_e32 v216, 16, v175
	v_and_b32_e32 v217, 0xffff0000, v175
	v_add_f32_e32 v32, v32, v214
	v_add_f32_e32 v33, v33, v215
	v_add_f32_e32 v34, v34, v216
	v_add_f32_e32 v35, v35, v217
	v_mul_f32_e32 v218, v33, v33
	v_mul_f32_e32 v219, v35, v35
	v_fmac_f32_e32 v218, v32, v32
	v_fmac_f32_e32 v219, v34, v34
	v_add_f32_e32 v223, v218, v219
	v_cvt_pk_bf16_f32 v36, v36, v37
	v_cvt_pk_bf16_f32 v37, v38, v39
	v_cvt_pk_bf16_f32 v38, v32, v33
	v_cvt_pk_bf16_f32 v39, v34, v35
	global_store_dwordx4 v230, v[36:39], s[10:11] offset:256
	v_add_f32_e32 v220, v220, v221
	v_add_f32_e32 v222, v222, v223
	v_add_f32_e32 v224, v220, v222
	v_add_u32_e32 v231, 0x2400, v227
	v_mov_b32_e32 v225, v224
	s_nop 1
	v_permlane16_swap_b32_e32 v224, v225
	v_add_f32_e32 v224, v224, v225
	v_mov_b32_e32 v225, v224
	s_nop 1
	v_permlane32_swap_b32_e32 v224, v225
	v_add_f32_e32 v224, v224, v225
	s_and_saveexec_b64 s[0:1], vcc
	global_store_dword v231, v224, s[12:13]
	s_or_b64 exec, exec, s[0:1]
	s_waitcnt vmcnt(20)
	v_lshlrev_b32_e32 v214, 16, v176
	v_and_b32_e32 v215, 0xffff0000, v176
	v_lshlrev_b32_e32 v216, 16, v177
	v_and_b32_e32 v217, 0xffff0000, v177
	v_add_f32_e32 v28, v28, v214
	v_add_f32_e32 v29, v29, v215
	v_add_f32_e32 v30, v30, v216
	v_add_f32_e32 v31, v31, v217
	v_mul_f32_e32 v218, v29, v29
	v_mul_f32_e32 v219, v31, v31
	v_fmac_f32_e32 v218, v28, v28
	v_fmac_f32_e32 v219, v30, v30
	v_add_f32_e32 v220, v218, v219
	v_lshlrev_b32_e32 v214, 16, v178
	v_and_b32_e32 v215, 0xffff0000, v178
	v_lshlrev_b32_e32 v216, 16, v179
	v_and_b32_e32 v217, 0xffff0000, v179
	v_add_f32_e32 v24, v24, v214
	v_add_f32_e32 v25, v25, v215
	v_add_f32_e32 v26, v26, v216
	v_add_f32_e32 v27, v27, v217
	v_mul_f32_e32 v218, v25, v25
	v_mul_f32_e32 v219, v27, v27
	v_fmac_f32_e32 v218, v24, v24
	v_fmac_f32_e32 v219, v26, v26
	v_add_f32_e32 v221, v218, v219
	v_cvt_pk_bf16_f32 v28, v28, v29
	v_cvt_pk_bf16_f32 v29, v30, v31
	v_cvt_pk_bf16_f32 v30, v24, v25
	v_cvt_pk_bf16_f32 v31, v26, v27
	v_add_u32_e32 v230, 0x50000, v226
	global_store_dwordx4 v230, v[28:31], s[10:11]
	v_lshlrev_b32_e32 v214, 16, v180
	v_and_b32_e32 v215, 0xffff0000, v180
	v_lshlrev_b32_e32 v216, 16, v181
	v_and_b32_e32 v217, 0xffff0000, v181
	v_add_f32_e32 v20, v20, v214
	v_add_f32_e32 v21, v21, v215
	v_add_f32_e32 v22, v22, v216
	v_add_f32_e32 v23, v23, v217
	v_mul_f32_e32 v218, v21, v21
	v_mul_f32_e32 v219, v23, v23
	v_fmac_f32_e32 v218, v20, v20
	v_fmac_f32_e32 v219, v22, v22
	v_add_f32_e32 v222, v218, v219
	v_lshlrev_b32_e32 v214, 16, v182
	v_and_b32_e32 v215, 0xffff0000, v182
	v_lshlrev_b32_e32 v216, 16, v183
	v_and_b32_e32 v217, 0xffff0000, v183
	v_add_f32_e32 v16, v16, v214
	v_add_f32_e32 v17, v17, v215
	v_add_f32_e32 v18, v18, v216
	v_add_f32_e32 v19, v19, v217
	v_mul_f32_e32 v218, v17, v17
	v_mul_f32_e32 v219, v19, v19
	v_fmac_f32_e32 v218, v16, v16
	v_fmac_f32_e32 v219, v18, v18
	v_add_f32_e32 v223, v218, v219
	v_cvt_pk_bf16_f32 v20, v20, v21
	v_cvt_pk_bf16_f32 v21, v22, v23
	v_cvt_pk_bf16_f32 v22, v16, v17
	v_cvt_pk_bf16_f32 v23, v18, v19
	global_store_dwordx4 v230, v[20:23], s[10:11] offset:256
	v_add_f32_e32 v220, v220, v221
	v_add_f32_e32 v222, v222, v223
	v_add_f32_e32 v224, v220, v222
	v_add_u32_e32 v231, 0x2800, v227
	v_mov_b32_e32 v225, v224
	s_nop 1
	v_permlane16_swap_b32_e32 v224, v225
	v_add_f32_e32 v224, v224, v225
	v_mov_b32_e32 v225, v224
	s_nop 1
	v_permlane32_swap_b32_e32 v224, v225
	v_add_f32_e32 v224, v224, v225
	s_and_saveexec_b64 s[0:1], vcc
	global_store_dword v231, v224, s[12:13]
	s_or_b64 exec, exec, s[0:1]
	s_waitcnt vmcnt(21)
; __device__ __forceinline__ u32x4 pack8(const f32x4 v0, const f32x4 v1) { u32x4 w; w.x = cvt_pk_bf16(v0[0], v0[1]); w.y = cvt_pk_bf16(v0[2], v0[3]); w.z = cvt_pk_bf16(v1[0], v1[1]); w.w = cvt_pk_bf16(v1[2], v1[3]); return w; }
; __device__ __forceinline__ float sumsq8(const f32x4 a, const f32x4 b) { return ((a[0] * a[0] + a[1] * a[1]) + (a[2] * a[2] + a[3] * a[3])) + ((b[0] * b[0] + b[1] * b[1]) + (b[2] * b[2] + b[3] * b[3])); }
; __device__ __forceinline__ void unpack8(const u32x4 w, f32x4& a, f32x4& b) { a = (f32x4){bf_lo(w.x), bf_hi(w.x), bf_lo(w.y), bf_hi(w.y)}; b = (f32x4){bf_lo(w.z), bf_hi(w.z), bf_lo(w.w), bf_hi(w.w)}; }
; #define PG8_BAR __builtin_amdgcn_s_barrier()
;     __device__ __forceinline__ void operator()(const f32x4 (&acc)[2][2][4][2], const Unit& u, int wr, int wc, int fr, int fq) const {
;     ...
; #pragma unroll
;         for (int ai = 0; ai < 2; ++ai)
; #pragma unroll
;             for (int m = 0; m < 4; ++m) { const int row = row0 + ai * HALF + m * 16; float part = 0.f;
; #pragma unroll
;                 for (int bj = 0; bj < 2; ++bj) { f32x4 r0, r1; unpack8(rv[ai * 4 + m][bj], r0, r1);
;                     const f32x4 h0 = r0 + acc[ai][bj][m][0], h1 = r1 + acc[ai][bj][m][1]; part += sumsq8(h0, h1);
;                     *(u32x4*)(XBo + (size_t)row * DMODEL + col0 + bj * HALF) = pack8(h0, h1); }
;                 part += __shfl_xor(part, 16); part += __shfl_xor(part, 32);
;                 if (fq == 0) ssq[(size_t)row * 16 + u.pn * 4 + wc] = part; }
; template <class Epi, class Sched, bool ALIGN_EPI = false, bool SP2 = false>
; __device__ __forceinline__ void gemm_phase(PG8_LAS unsigned char* lds, const Gemm g, const Sched& S, const Epi& E) {
;     ...
;         if (!has_next) break;
; #pragma unroll
;         for (int a = 0; a < 2; ++a)
; #pragma unroll
;             for (int b = 0; b < 2; ++b)
; #pragma unroll
;                 for (int m = 0; m < 4; ++m)
; #pragma unroll
;                     for (int n = 0; n < 2; ++n) acc[a][b][m][n] = (f32x4){0.f, 0.f, 0.f, 0.f};
;         cur = nxt; cA = nA; cB = nB; ++ui; relax = Epi::LOADS_BEFORE_STORES && !Epi::AFTER_DRAIN && SP2;
;         if constexpr (ALIGN_EPI) { if (wr == 1) PG8_BAR; }
	v_lshlrev_b32_e32 v214, 16, v184
	v_and_b32_e32 v215, 0xffff0000, v184
	v_lshlrev_b32_e32 v216, 16, v185
	v_and_b32_e32 v217, 0xffff0000, v185
	v_add_f32_e32 v12, v12, v214
	v_add_f32_e32 v13, v13, v215
	v_add_f32_e32 v14, v14, v216
	v_add_f32_e32 v15, v15, v217
	v_mul_f32_e32 v218, v13, v13
	v_mul_f32_e32 v219, v15, v15
	v_fmac_f32_e32 v218, v12, v12
	v_fmac_f32_e32 v219, v14, v14
	v_add_f32_e32 v220, v218, v219
	v_lshlrev_b32_e32 v214, 16, v186
	v_and_b32_e32 v215, 0xffff0000, v186
	v_lshlrev_b32_e32 v216, 16, v187
	v_and_b32_e32 v217, 0xffff0000, v187
	v_add_f32_e32 v8, v8, v214
	v_add_f32_e32 v9, v9, v215
	v_add_f32_e32 v10, v10, v216
	v_add_f32_e32 v11, v11, v217
	v_mul_f32_e32 v218, v9, v9
	v_mul_f32_e32 v219, v11, v11
	v_fmac_f32_e32 v218, v8, v8
	v_fmac_f32_e32 v219, v10, v10
	v_add_f32_e32 v221, v218, v219
	v_cvt_pk_bf16_f32 v12, v12, v13
	v_cvt_pk_bf16_f32 v13, v14, v15
	v_cvt_pk_bf16_f32 v14, v8, v9
	v_cvt_pk_bf16_f32 v15, v10, v11
	v_add_u32_e32 v230, 0x58000, v226
	global_store_dwordx4 v230, v[12:15], s[10:11]
	v_lshlrev_b32_e32 v214, 16, v188
	v_and_b32_e32 v215, 0xffff0000, v188
	v_lshlrev_b32_e32 v216, 16, v189
	v_and_b32_e32 v217, 0xffff0000, v189
	v_add_f32_e32 v4, v4, v214
	v_add_f32_e32 v5, v5, v215
	v_add_f32_e32 v6, v6, v216
	v_add_f32_e32 v7, v7, v217
	v_mul_f32_e32 v218, v5, v5
	v_mul_f32_e32 v219, v7, v7
	v_fmac_f32_e32 v218, v4, v4
	v_fmac_f32_e32 v219, v6, v6
	v_add_f32_e32 v222, v218, v219
	v_lshlrev_b32_e32 v214, 16, v190
	v_and_b32_e32 v215, 0xffff0000, v190
	v_lshlrev_b32_e32 v216, 16, v191
	v_and_b32_e32 v217, 0xffff0000, v191
	v_add_f32_e32 v0, v0, v214
	v_add_f32_e32 v1, v1, v215
	v_add_f32_e32 v2, v2, v216
	v_add_f32_e32 v3, v3, v217
	v_mul_f32_e32 v218, v1, v1
	v_mul_f32_e32 v219, v3, v3
	v_fmac_f32_e32 v218, v0, v0
	v_fmac_f32_e32 v219, v2, v2
	v_add_f32_e32 v223, v218, v219
	v_cvt_pk_bf16_f32 v4, v4, v5
	v_cvt_pk_bf16_f32 v5, v6, v7
	v_cvt_pk_bf16_f32 v6, v0, v1
	v_cvt_pk_bf16_f32 v7, v2, v3
	global_store_dwordx4 v230, v[4:7], s[10:11] offset:256
	v_add_f32_e32 v220, v220, v221
	v_add_f32_e32 v222, v222, v223
	v_add_f32_e32 v224, v220, v222
	v_add_u32_e32 v231, 0x2c00, v227
	v_mov_b32_e32 v225, v224
	s_nop 1
	v_permlane16_swap_b32_e32 v224, v225
	v_add_f32_e32 v224, v224, v225
	v_mov_b32_e32 v225, v224
	s_nop 1
	v_permlane32_swap_b32_e32 v224, v225
	v_add_f32_e32 v224, v224, v225
	s_and_saveexec_b64 s[0:1], vcc
	global_store_dword v231, v224, s[12:13]
	s_or_b64 exec, exec, s[0:1]
	s_mov_b64 s[42:43], -1
	s_andn2_b64 vcc, exec, s[20:21]
	s_mov_b64 s[0:1], -1
	s_cbranch_vccnz .LBB0_504
	s_andn2_b64 vcc, exec, s[8:9]
	s_cbranch_vccnz .LBB0_503
	s_barrier
	s_branch .LBB0_503

; __device__ __forceinline__ u32x4 pack8(const f32x4 v0, const f32x4 v1) { u32x4 w; w.x = cvt_pk_bf16(v0[0], v0[1]); w.y = cvt_pk_bf16(v0[2], v0[3]); w.z = cvt_pk_bf16(v1[0], v1[1]); w.w = cvt_pk_bf16(v1[2], v1[3]); return w; }
; __device__ __forceinline__ float sumsq8(const f32x4 a, const f32x4 b) { return ((a[0] * a[0] + a[1] * a[1]) + (a[2] * a[2] + a[3] * a[3])) + ((b[0] * b[0] + b[1] * b[1]) + (b[2] * b[2] + b[3] * b[3])); }
; __device__ __forceinline__ void unpack8(const u32x4 w, f32x4& a, f32x4& b) { a = (f32x4){bf_lo(w.x), bf_hi(w.x), bf_lo(w.y), bf_hi(w.y)}; b = (f32x4){bf_lo(w.z), bf_hi(w.z), bf_lo(w.w), bf_hi(w.w)}; }
;     __device__ __forceinline__ void operator()(const f32x4 (&acc)[2][2][4][2], const Unit& u, int wr, int wc, int fr, int fq) const {
;         const int row0 = u.pm * BM + wr * 64 + fr, col0 = u.pn * BM + wc * 32 + 8 * fq;
;         u32x4 rv[8][2];
; #pragma unroll
;         for (int i = 0; i < 8; ++i)
; #pragma unroll
;             for (int bj = 0; bj < 2; ++bj) rv[i][bj] = *(const u32x4*)(Rin + (size_t)(row0 + (i >> 2) * HALF + (i & 3) * 16) * DMODEL + col0 + bj * HALF);
; #pragma unroll
;         for (int ai = 0; ai < 2; ++ai)
; #pragma unroll
;             for (int m = 0; m < 4; ++m) { const int row = row0 + ai * HALF + m * 16; float part = 0.f;
; #pragma unroll
;                 for (int bj = 0; bj < 2; ++bj) { f32x4 r0, r1; unpack8(rv[ai * 4 + m][bj], r0, r1);
;                     const f32x4 h0 = r0 + acc[ai][bj][m][0], h1 = r1 + acc[ai][bj][m][1]; part += sumsq8(h0, h1);
;                     *(u32x4*)(XBo + (size_t)row * DMODEL + col0 + bj * HALF) = pack8(h0, h1); }
;                 part += __shfl_xor(part, 16); part += __shfl_xor(part, 32);
;                 if (fq == 0) ssq[(size_t)row * 16 + u.pn * 4 + wc] = part; }
.LBB0_968:
	v_readfirstlane_b32 s0, v192
	v_and_b32_e32 v224, 15, v192
	s_bfe_u32 s13, s0, 0x20006
	s_lshr_b32 s0, s0, 8
	s_lshl_b32 s0, s0, 6
	s_lshl_b32 s1, s24, 8
	s_add_i32 s0, s0, s1
	v_add_u32_e32 v224, s0, v224
	v_bfe_u32 v225, v192, 4, 2
	s_lshl_b32 s0, s22, 8
	s_lshl_b32 s1, s13, 5
	s_or_b32 s0, s0, s1
	v_lshl_or_b32 v232, v225, 3, s0
	v_lshlrev_b32_e32 v226, 11, v224
	v_lshl_add_u32 v226, v232, 1, v226
	v_mov_b32_e32 v230, v226
	global_load_dwordx4 v[116:119], v230, s[6:7]
	global_load_dwordx4 v[120:123], v230, s[6:7] offset:256
	v_add_u32_e32 v230, 0x8000, v226
	global_load_dwordx4 v[128:131], v230, s[6:7]
	global_load_dwordx4 v[132:135], v230, s[6:7] offset:256
	v_add_u32_e32 v230, 0x10000, v226
	global_load_dwordx4 v[136:139], v230, s[6:7]
	global_load_dwordx4 v[140:143], v230, s[6:7] offset:256
	v_add_u32_e32 v230, 0x18000, v226
	global_load_dwordx4 v[144:147], v230, s[6:7]
	global_load_dwordx4 v[156:159], v230, s[6:7] offset:256
	v_add_u32_e32 v230, 0x40000, v226
	global_load_dwordx4 v[160:163], v230, s[6:7]
	global_load_dwordx4 v[164:167], v230, s[6:7] offset:256
	v_add_u32_e32 v230, 0x48000, v226
	global_load_dwordx4 v[168:171], v230, s[6:7]
	global_load_dwordx4 v[172:175], v230, s[6:7] offset:256
	v_add_u32_e32 v230, 0x50000, v226
	global_load_dwordx4 v[176:179], v230, s[6:7]
	global_load_dwordx4 v[180:183], v230, s[6:7] offset:256
	v_add_u32_e32 v230, 0x58000, v226
	global_load_dwordx4 v[184:187], v230, s[6:7]
	global_load_dwordx4 v[188:191], v230, s[6:7] offset:256
	v_lshlrev_b32_e32 v227, 6, v224
	s_lshl_b32 s22, s22, 2
	s_ashr_i32 s23, s22, 31
	s_lshl_b32 s72, s13, 2
	s_lshl_b32 s0, s22, 2
	s_add_i32 s0, s0, s72
	v_add_u32_e32 v227, s0, v227
	v_cmp_eq_u32_e32 vcc, 0, v225
	v_xor_b32_e32 v228, 16, v241
	v_xor_b32_e32 v229, 32, v241
	v_lshlrev_b32_e32 v228, 2, v228
	v_lshlrev_b32_e32 v229, 2, v229
	s_waitcnt vmcnt(14)
	v_lshlrev_b32_e32 v214, 16, v116
	v_and_b32_e32 v215, 0xffff0000, v116
	v_lshlrev_b32_e32 v216, 16, v117
	v_and_b32_e32 v217, 0xffff0000, v117
	v_add_f32_e32 v152, v152, v214
	v_add_f32_e32 v153, v153, v215
	v_add_f32_e32 v154, v154, v216
	v_add_f32_e32 v155, v155, v217
	v_mul_f32_e32 v218, v153, v153
	v_mul_f32_e32 v219, v155, v155
	v_fmac_f32_e32 v218, v152, v152
	v_fmac_f32_e32 v219, v154, v154
	v_add_f32_e32 v220, v218, v219
	v_lshlrev_b32_e32 v214, 16, v118
	v_and_b32_e32 v215, 0xffff0000, v118
	v_lshlrev_b32_e32 v216, 16, v119
	v_and_b32_e32 v217, 0xffff0000, v119
	v_add_f32_e32 v148, v148, v214
	v_add_f32_e32 v149, v149, v215
	v_add_f32_e32 v150, v150, v216
	v_add_f32_e32 v151, v151, v217
	v_mul_f32_e32 v218, v149, v149
	v_mul_f32_e32 v219, v151, v151
	v_fmac_f32_e32 v218, v148, v148
	v_fmac_f32_e32 v219, v150, v150
	v_add_f32_e32 v221, v218, v219
	v_cvt_pk_bf16_f32 v152, v152, v153
	v_cvt_pk_bf16_f32 v153, v154, v155
	v_cvt_pk_bf16_f32 v154, v148, v149
	v_cvt_pk_bf16_f32 v155, v150, v151
	v_mov_b32_e32 v230, v226
	global_store_dwordx4 v230, v[152:155], s[6:7]
	v_lshlrev_b32_e32 v214, 16, v120
	v_and_b32_e32 v215, 0xffff0000, v120
	v_lshlrev_b32_e32 v216, 16, v121
	v_and_b32_e32 v217, 0xffff0000, v121
	v_add_f32_e32 v124, v124, v214
	v_add_f32_e32 v125, v125, v215
	v_add_f32_e32 v126, v126, v216
	v_add_f32_e32 v127, v127, v217
	v_mul_f32_e32 v218, v125, v125
	v_mul_f32_e32 v219, v127, v127
	v_fmac_f32_e32 v218, v124, v124
	v_fmac_f32_e32 v219, v126, v126
	v_add_f32_e32 v222, v218, v219
	v_lshlrev_b32_e32 v214, 16, v122
	v_and_b32_e32 v215, 0xffff0000, v122
	v_lshlrev_b32_e32 v216, 16, v123
	v_and_b32_e32 v217, 0xffff0000, v123
	v_add_f32_e32 v112, v112, v214
	v_add_f32_e32 v113, v113, v215
	v_add_f32_e32 v114, v114, v216
	v_add_f32_e32 v115, v115, v217
	v_mul_f32_e32 v218, v113, v113
	v_mul_f32_e32 v219, v115, v115
	v_fmac_f32_e32 v218, v112, v112
	v_fmac_f32_e32 v219, v114, v114
	v_add_f32_e32 v223, v218, v219
	v_cvt_pk_bf16_f32 v124, v124, v125
	v_cvt_pk_bf16_f32 v125, v126, v127
	v_cvt_pk_bf16_f32 v126, v112, v113
	v_cvt_pk_bf16_f32 v127, v114, v115
	global_store_dwordx4 v230, v[124:127], s[6:7] offset:256
	v_add_f32_e32 v220, v220, v221
	v_add_f32_e32 v222, v222, v223
	v_add_f32_e32 v224, v220, v222
	v_mov_b32_e32 v231, v227
	v_mov_b32_e32 v225, v224
	s_nop 1
	v_permlane16_swap_b32_e32 v224, v225
	v_add_f32_e32 v224, v224, v225
	v_mov_b32_e32 v225, v224
	s_nop 1
	v_permlane32_swap_b32_e32 v224, v225
	v_add_f32_e32 v224, v224, v225
	s_and_saveexec_b64 s[0:1], vcc
	global_store_dword v231, v224, s[8:9]
	s_or_b64 exec, exec, s[0:1]
	s_waitcnt vmcnt(15)
; __device__ __forceinline__ u32x4 pack8(const f32x4 v0, const f32x4 v1) { u32x4 w; w.x = cvt_pk_bf16(v0[0], v0[1]); w.y = cvt_pk_bf16(v0[2], v0[3]); w.z = cvt_pk_bf16(v1[0], v1[1]); w.w = cvt_pk_bf16(v1[2], v1[3]); return w; }
; __device__ __forceinline__ float sumsq8(const f32x4 a, const f32x4 b) { return ((a[0] * a[0] + a[1] * a[1]) + (a[2] * a[2] + a[3] * a[3])) + ((b[0] * b[0] + b[1] * b[1]) + (b[2] * b[2] + b[3] * b[3])); }
; __device__ __forceinline__ void unpack8(const u32x4 w, f32x4& a, f32x4& b) { a = (f32x4){bf_lo(w.x), bf_hi(w.x), bf_lo(w.y), bf_hi(w.y)}; b = (f32x4){bf_lo(w.z), bf_hi(w.z), bf_lo(w.w), bf_hi(w.w)}; }
;     __device__ __forceinline__ void operator()(const f32x4 (&acc)[2][2][4][2], const Unit& u, int wr, int wc, int fr, int fq) const {
;     ...
; #pragma unroll
;         for (int ai = 0; ai < 2; ++ai)
; #pragma unroll
;             for (int m = 0; m < 4; ++m) { const int row = row0 + ai * HALF + m * 16; float part = 0.f;
; #pragma unroll
;                 for (int bj = 0; bj < 2; ++bj) { f32x4 r0, r1; unpack8(rv[ai * 4 + m][bj], r0, r1);
;                     const f32x4 h0 = r0 + acc[ai][bj][m][0], h1 = r1 + acc[ai][bj][m][1]; part += sumsq8(h0, h1);
;                     *(u32x4*)(XBo + (size_t)row * DMODEL + col0 + bj * HALF) = pack8(h0, h1); }
;                 part += __shfl_xor(part, 16); part += __shfl_xor(part, 32);
;                 if (fq == 0) ssq[(size_t)row * 16 + u.pn * 4 + wc] = part; }
	v_lshlrev_b32_e32 v214, 16, v128
	v_and_b32_e32 v215, 0xffff0000, v128
	v_lshlrev_b32_e32 v216, 16, v129
	v_and_b32_e32 v217, 0xffff0000, v129
	v_add_f32_e32 v108, v108, v214
	v_add_f32_e32 v109, v109, v215
	v_add_f32_e32 v110, v110, v216
	v_add_f32_e32 v111, v111, v217
	v_mul_f32_e32 v218, v109, v109
	v_mul_f32_e32 v219, v111, v111
	v_fmac_f32_e32 v218, v108, v108
	v_fmac_f32_e32 v219, v110, v110
	v_add_f32_e32 v220, v218, v219
	v_lshlrev_b32_e32 v214, 16, v130
	v_and_b32_e32 v215, 0xffff0000, v130
	v_lshlrev_b32_e32 v216, 16, v131
	v_and_b32_e32 v217, 0xffff0000, v131
	v_add_f32_e32 v104, v104, v214
	v_add_f32_e32 v105, v105, v215
	v_add_f32_e32 v106, v106, v216
	v_add_f32_e32 v107, v107, v217
	v_mul_f32_e32 v218, v105, v105
	v_mul_f32_e32 v219, v107, v107
	v_fmac_f32_e32 v218, v104, v104
	v_fmac_f32_e32 v219, v106, v106
	v_add_f32_e32 v221, v218, v219
	v_cvt_pk_bf16_f32 v108, v108, v109
	v_cvt_pk_bf16_f32 v109, v110, v111
	v_cvt_pk_bf16_f32 v110, v104, v105
	v_cvt_pk_bf16_f32 v111, v106, v107
	v_add_u32_e32 v230, 0x8000, v226
	global_store_dwordx4 v230, v[108:111], s[6:7]
	v_lshlrev_b32_e32 v214, 16, v132
	v_and_b32_e32 v215, 0xffff0000, v132
	v_lshlrev_b32_e32 v216, 16, v133
	v_and_b32_e32 v217, 0xffff0000, v133
	v_add_f32_e32 v100, v100, v214
	v_add_f32_e32 v101, v101, v215
	v_add_f32_e32 v102, v102, v216
	v_add_f32_e32 v103, v103, v217
	v_mul_f32_e32 v218, v101, v101
	v_mul_f32_e32 v219, v103, v103
	v_fmac_f32_e32 v218, v100, v100
	v_fmac_f32_e32 v219, v102, v102
	v_add_f32_e32 v222, v218, v219
	v_lshlrev_b32_e32 v214, 16, v134
	v_and_b32_e32 v215, 0xffff0000, v134
	v_lshlrev_b32_e32 v216, 16, v135
	v_and_b32_e32 v217, 0xffff0000, v135
	v_add_f32_e32 v96, v96, v214
	v_add_f32_e32 v97, v97, v215
	v_add_f32_e32 v98, v98, v216
	v_add_f32_e32 v99, v99, v217
	v_mul_f32_e32 v218, v97, v97
	v_mul_f32_e32 v219, v99, v99
	v_fmac_f32_e32 v218, v96, v96
	v_fmac_f32_e32 v219, v98, v98
	v_add_f32_e32 v223, v218, v219
	v_cvt_pk_bf16_f32 v100, v100, v101
	v_cvt_pk_bf16_f32 v101, v102, v103
	v_cvt_pk_bf16_f32 v102, v96, v97
	v_cvt_pk_bf16_f32 v103, v98, v99
	global_store_dwordx4 v230, v[100:103], s[6:7] offset:256
	v_add_f32_e32 v220, v220, v221
	v_add_f32_e32 v222, v222, v223
	v_add_f32_e32 v224, v220, v222
	v_add_u32_e32 v231, 0x400, v227
	v_mov_b32_e32 v225, v224
	s_nop 1
	v_permlane16_swap_b32_e32 v224, v225
	v_add_f32_e32 v224, v224, v225
	v_mov_b32_e32 v225, v224
	s_nop 1
	v_permlane32_swap_b32_e32 v224, v225
	v_add_f32_e32 v224, v224, v225
	s_and_saveexec_b64 s[0:1], vcc
	global_store_dword v231, v224, s[8:9]
	s_or_b64 exec, exec, s[0:1]
	s_waitcnt vmcnt(16)
	v_lshlrev_b32_e32 v214, 16, v136
	v_and_b32_e32 v215, 0xffff0000, v136
	v_lshlrev_b32_e32 v216, 16, v137
	v_and_b32_e32 v217, 0xffff0000, v137
	v_add_f32_e32 v92, v92, v214
	v_add_f32_e32 v93, v93, v215
	v_add_f32_e32 v94, v94, v216
	v_add_f32_e32 v95, v95, v217
	v_mul_f32_e32 v218, v93, v93
	v_mul_f32_e32 v219, v95, v95
	v_fmac_f32_e32 v218, v92, v92
	v_fmac_f32_e32 v219, v94, v94
	v_add_f32_e32 v220, v218, v219
	v_lshlrev_b32_e32 v214, 16, v138
	v_and_b32_e32 v215, 0xffff0000, v138
	v_lshlrev_b32_e32 v216, 16, v139
	v_and_b32_e32 v217, 0xffff0000, v139
	v_add_f32_e32 v88, v88, v214
	v_add_f32_e32 v89, v89, v215
	v_add_f32_e32 v90, v90, v216
	v_add_f32_e32 v91, v91, v217
	v_mul_f32_e32 v218, v89, v89
	v_mul_f32_e32 v219, v91, v91
	v_fmac_f32_e32 v218, v88, v88
	v_fmac_f32_e32 v219, v90, v90
	v_add_f32_e32 v221, v218, v219
	v_cvt_pk_bf16_f32 v92, v92, v93
	v_cvt_pk_bf16_f32 v93, v94, v95
	v_cvt_pk_bf16_f32 v94, v88, v89
	v_cvt_pk_bf16_f32 v95, v90, v91
	v_add_u32_e32 v230, 0x10000, v226
	global_store_dwordx4 v230, v[92:95], s[6:7]
	v_lshlrev_b32_e32 v214, 16, v140
	v_and_b32_e32 v215, 0xffff0000, v140
	v_lshlrev_b32_e32 v216, 16, v141
	v_and_b32_e32 v217, 0xffff0000, v141
	v_add_f32_e32 v84, v84, v214
	v_add_f32_e32 v85, v85, v215
	v_add_f32_e32 v86, v86, v216
	v_add_f32_e32 v87, v87, v217
	v_mul_f32_e32 v218, v85, v85
	v_mul_f32_e32 v219, v87, v87
	v_fmac_f32_e32 v218, v84, v84
	v_fmac_f32_e32 v219, v86, v86
	v_add_f32_e32 v222, v218, v219
	v_lshlrev_b32_e32 v214, 16, v142
	v_and_b32_e32 v215, 0xffff0000, v142
	v_lshlrev_b32_e32 v216, 16, v143
	v_and_b32_e32 v217, 0xffff0000, v143
	v_add_f32_e32 v80, v80, v214
	v_add_f32_e32 v81, v81, v215
	v_add_f32_e32 v82, v82, v216
	v_add_f32_e32 v83, v83, v217
	v_mul_f32_e32 v218, v81, v81
	v_mul_f32_e32 v219, v83, v83
	v_fmac_f32_e32 v218, v80, v80
	v_fmac_f32_e32 v219, v82, v82
	v_add_f32_e32 v223, v218, v219
	v_cvt_pk_bf16_f32 v84, v84, v85
	v_cvt_pk_bf16_f32 v85, v86, v87
	v_cvt_pk_bf16_f32 v86, v80, v81
	v_cvt_pk_bf16_f32 v87, v82, v83
	global_store_dwordx4 v230, v[84:87], s[6:7] offset:256
	v_add_f32_e32 v220, v220, v221
	v_add_f32_e32 v222, v222, v223
	v_add_f32_e32 v224, v220, v222
	v_add_u32_e32 v231, 0x800, v227
	v_mov_b32_e32 v225, v224
	s_nop 1
	v_permlane16_swap_b32_e32 v224, v225
	v_add_f32_e32 v224, v224, v225
	v_mov_b32_e32 v225, v224
	s_nop 1
	v_permlane32_swap_b32_e32 v224, v225
	v_add_f32_e32 v224, v224, v225
	s_and_saveexec_b64 s[0:1], vcc
	global_store_dword v231, v224, s[8:9]
	s_or_b64 exec, exec, s[0:1]
	s_waitcnt vmcnt(17)
; __device__ __forceinline__ u32x4 pack8(const f32x4 v0, const f32x4 v1) { u32x4 w; w.x = cvt_pk_bf16(v0[0], v0[1]); w.y = cvt_pk_bf16(v0[2], v0[3]); w.z = cvt_pk_bf16(v1[0], v1[1]); w.w = cvt_pk_bf16(v1[2], v1[3]); return w; }
; __device__ __forceinline__ float sumsq8(const f32x4 a, const f32x4 b) { return ((a[0] * a[0] + a[1] * a[1]) + (a[2] * a[2] + a[3] * a[3])) + ((b[0] * b[0] + b[1] * b[1]) + (b[2] * b[2] + b[3] * b[3])); }
; __device__ __forceinline__ void unpack8(const u32x4 w, f32x4& a, f32x4& b) { a = (f32x4){bf_lo(w.x), bf_hi(w.x), bf_lo(w.y), bf_hi(w.y)}; b = (f32x4){bf_lo(w.z), bf_hi(w.z), bf_lo(w.w), bf_hi(w.w)}; }
;     __device__ __forceinline__ void operator()(const f32x4 (&acc)[2][2][4][2], const Unit& u, int wr, int wc, int fr, int fq) const {
;     ...
; #pragma unroll
;         for (int ai = 0; ai < 2; ++ai)
; #pragma unroll
;             for (int m = 0; m < 4; ++m) { const int row = row0 + ai * HALF + m * 16; float part = 0.f;
; #pragma unroll
;                 for (int bj = 0; bj < 2; ++bj) { f32x4 r0, r1; unpack8(rv[ai * 4 + m][bj], r0, r1);
;                     const f32x4 h0 = r0 + acc[ai][bj][m][0], h1 = r1 + acc[ai][bj][m][1]; part += sumsq8(h0, h1);
;                     *(u32x4*)(XBo + (size_t)row * DMODEL + col0 + bj * HALF) = pack8(h0, h1); }
;                 part += __shfl_xor(part, 16); part += __shfl_xor(part, 32);
;                 if (fq == 0) ssq[(size_t)row * 16 + u.pn * 4 + wc] = part; }
	v_lshlrev_b32_e32 v214, 16, v144
	v_and_b32_e32 v215, 0xffff0000, v144
	v_lshlrev_b32_e32 v216, 16, v145
	v_and_b32_e32 v217, 0xffff0000, v145
	v_add_f32_e32 v76, v76, v214
	v_add_f32_e32 v77, v77, v215
	v_add_f32_e32 v78, v78, v216
	v_add_f32_e32 v79, v79, v217
	v_mul_f32_e32 v218, v77, v77
	v_mul_f32_e32 v219, v79, v79
	v_fmac_f32_e32 v218, v76, v76
	v_fmac_f32_e32 v219, v78, v78
	v_add_f32_e32 v220, v218, v219
	v_lshlrev_b32_e32 v214, 16, v146
	v_and_b32_e32 v215, 0xffff0000, v146
	v_lshlrev_b32_e32 v216, 16, v147
	v_and_b32_e32 v217, 0xffff0000, v147
	v_add_f32_e32 v72, v72, v214
	v_add_f32_e32 v73, v73, v215
	v_add_f32_e32 v74, v74, v216
	v_add_f32_e32 v75, v75, v217
	v_mul_f32_e32 v218, v73, v73
	v_mul_f32_e32 v219, v75, v75
	v_fmac_f32_e32 v218, v72, v72
	v_fmac_f32_e32 v219, v74, v74
	v_add_f32_e32 v221, v218, v219
	v_cvt_pk_bf16_f32 v76, v76, v77
	v_cvt_pk_bf16_f32 v77, v78, v79
	v_cvt_pk_bf16_f32 v78, v72, v73
	v_cvt_pk_bf16_f32 v79, v74, v75
	v_add_u32_e32 v230, 0x18000, v226
	global_store_dwordx4 v230, v[76:79], s[6:7]
	v_lshlrev_b32_e32 v214, 16, v156
	v_and_b32_e32 v215, 0xffff0000, v156
	v_lshlrev_b32_e32 v216, 16, v157
	v_and_b32_e32 v217, 0xffff0000, v157
	v_add_f32_e32 v68, v68, v214
	v_add_f32_e32 v69, v69, v215
	v_add_f32_e32 v70, v70, v216
	v_add_f32_e32 v71, v71, v217
	v_mul_f32_e32 v218, v69, v69
	v_mul_f32_e32 v219, v71, v71
	v_fmac_f32_e32 v218, v68, v68
	v_fmac_f32_e32 v219, v70, v70
	v_add_f32_e32 v222, v218, v219
	v_lshlrev_b32_e32 v214, 16, v158
	v_and_b32_e32 v215, 0xffff0000, v158
	v_lshlrev_b32_e32 v216, 16, v159
	v_and_b32_e32 v217, 0xffff0000, v159
	v_add_f32_e32 v64, v64, v214
	v_add_f32_e32 v65, v65, v215
	v_add_f32_e32 v66, v66, v216
	v_add_f32_e32 v67, v67, v217
	v_mul_f32_e32 v218, v65, v65
	v_mul_f32_e32 v219, v67, v67
	v_fmac_f32_e32 v218, v64, v64
	v_fmac_f32_e32 v219, v66, v66
	v_add_f32_e32 v223, v218, v219
	v_cvt_pk_bf16_f32 v68, v68, v69
	v_cvt_pk_bf16_f32 v69, v70, v71
	v_cvt_pk_bf16_f32 v70, v64, v65
	v_cvt_pk_bf16_f32 v71, v66, v67
	global_store_dwordx4 v230, v[68:71], s[6:7] offset:256
	v_add_f32_e32 v220, v220, v221
	v_add_f32_e32 v222, v222, v223
	v_add_f32_e32 v224, v220, v222
	v_add_u32_e32 v231, 0xc00, v227
	v_mov_b32_e32 v225, v224
	s_nop 1
	v_permlane16_swap_b32_e32 v224, v225
	v_add_f32_e32 v224, v224, v225
	v_mov_b32_e32 v225, v224
	s_nop 1
	v_permlane32_swap_b32_e32 v224, v225
	v_add_f32_e32 v224, v224, v225
	s_and_saveexec_b64 s[0:1], vcc
	global_store_dword v231, v224, s[8:9]
	s_or_b64 exec, exec, s[0:1]
	s_waitcnt vmcnt(18)
	v_lshlrev_b32_e32 v214, 16, v160
	v_and_b32_e32 v215, 0xffff0000, v160
	v_lshlrev_b32_e32 v216, 16, v161
	v_and_b32_e32 v217, 0xffff0000, v161
	v_add_f32_e32 v60, v60, v214
	v_add_f32_e32 v61, v61, v215
	v_add_f32_e32 v62, v62, v216
	v_add_f32_e32 v63, v63, v217
	v_mul_f32_e32 v218, v61, v61
	v_mul_f32_e32 v219, v63, v63
	v_fmac_f32_e32 v218, v60, v60
	v_fmac_f32_e32 v219, v62, v62
	v_add_f32_e32 v220, v218, v219
	v_lshlrev_b32_e32 v214, 16, v162
	v_and_b32_e32 v215, 0xffff0000, v162
	v_lshlrev_b32_e32 v216, 16, v163
	v_and_b32_e32 v217, 0xffff0000, v163
	v_add_f32_e32 v56, v56, v214
	v_add_f32_e32 v57, v57, v215
	v_add_f32_e32 v58, v58, v216
	v_add_f32_e32 v59, v59, v217
	v_mul_f32_e32 v218, v57, v57
	v_mul_f32_e32 v219, v59, v59
	v_fmac_f32_e32 v218, v56, v56
	v_fmac_f32_e32 v219, v58, v58
	v_add_f32_e32 v221, v218, v219
	v_cvt_pk_bf16_f32 v60, v60, v61
	v_cvt_pk_bf16_f32 v61, v62, v63
	v_cvt_pk_bf16_f32 v62, v56, v57
	v_cvt_pk_bf16_f32 v63, v58, v59
	v_add_u32_e32 v230, 0x40000, v226
	global_store_dwordx4 v230, v[60:63], s[6:7]
	v_lshlrev_b32_e32 v214, 16, v164
	v_and_b32_e32 v215, 0xffff0000, v164
	v_lshlrev_b32_e32 v216, 16, v165
	v_and_b32_e32 v217, 0xffff0000, v165
	v_add_f32_e32 v52, v52, v214
	v_add_f32_e32 v53, v53, v215
	v_add_f32_e32 v54, v54, v216
	v_add_f32_e32 v55, v55, v217
	v_mul_f32_e32 v218, v53, v53
	v_mul_f32_e32 v219, v55, v55
	v_fmac_f32_e32 v218, v52, v52
	v_fmac_f32_e32 v219, v54, v54
	v_add_f32_e32 v222, v218, v219
	v_lshlrev_b32_e32 v214, 16, v166
	v_and_b32_e32 v215, 0xffff0000, v166
	v_lshlrev_b32_e32 v216, 16, v167
	v_and_b32_e32 v217, 0xffff0000, v167
	v_add_f32_e32 v48, v48, v214
	v_add_f32_e32 v49, v49, v215
	v_add_f32_e32 v50, v50, v216
	v_add_f32_e32 v51, v51, v217
	v_mul_f32_e32 v218, v49, v49
	v_mul_f32_e32 v219, v51, v51
	v_fmac_f32_e32 v218, v48, v48
	v_fmac_f32_e32 v219, v50, v50
	v_add_f32_e32 v223, v218, v219
	v_cvt_pk_bf16_f32 v52, v52, v53
	v_cvt_pk_bf16_f32 v53, v54, v55
	v_cvt_pk_bf16_f32 v54, v48, v49
	v_cvt_pk_bf16_f32 v55, v50, v51
	global_store_dwordx4 v230, v[52:55], s[6:7] offset:256
	v_add_f32_e32 v220, v220, v221
	v_add_f32_e32 v222, v222, v223
	v_add_f32_e32 v224, v220, v222
	v_add_u32_e32 v231, 0x2000, v227
	v_mov_b32_e32 v225, v224
	s_nop 1
	v_permlane16_swap_b32_e32 v224, v225
	v_add_f32_e32 v224, v224, v225
	v_mov_b32_e32 v225, v224
	s_nop 1
	v_permlane32_swap_b32_e32 v224, v225
	v_add_f32_e32 v224, v224, v225
	s_and_saveexec_b64 s[0:1], vcc
	global_store_dword v231, v224, s[8:9]
	s_or_b64 exec, exec, s[0:1]
	s_waitcnt vmcnt(19)
; __device__ __forceinline__ u32x4 pack8(const f32x4 v0, const f32x4 v1) { u32x4 w; w.x = cvt_pk_bf16(v0[0], v0[1]); w.y = cvt_pk_bf16(v0[2], v0[3]); w.z = cvt_pk_bf16(v1[0], v1[1]); w.w = cvt_pk_bf16(v1[2], v1[3]); return w; }
; __device__ __forceinline__ float sumsq8(const f32x4 a, const f32x4 b) { return ((a[0] * a[0] + a[1] * a[1]) + (a[2] * a[2] + a[3] * a[3])) + ((b[0] * b[0] + b[1] * b[1]) + (b[2] * b[2] + b[3] * b[3])); }
; __device__ __forceinline__ void unpack8(const u32x4 w, f32x4& a, f32x4& b) { a = (f32x4){bf_lo(w.x), bf_hi(w.x), bf_lo(w.y), bf_hi(w.y)}; b = (f32x4){bf_lo(w.z), bf_hi(w.z), bf_lo(w.w), bf_hi(w.w)}; }
;     __device__ __forceinline__ void operator()(const f32x4 (&acc)[2][2][4][2], const Unit& u, int wr, int wc, int fr, int fq) const {
;     ...
; #pragma unroll
;         for (int ai = 0; ai < 2; ++ai)
; #pragma unroll
;             for (int m = 0; m < 4; ++m) { const int row = row0 + ai * HALF + m * 16; float part = 0.f;
; #pragma unroll
;                 for (int bj = 0; bj < 2; ++bj) { f32x4 r0, r1; unpack8(rv[ai * 4 + m][bj], r0, r1);
;                     const f32x4 h0 = r0 + acc[ai][bj][m][0], h1 = r1 + acc[ai][bj][m][1]; part += sumsq8(h0, h1);
;                     *(u32x4*)(XBo + (size_t)row * DMODEL + col0 + bj * HALF) = pack8(h0, h1); }
;                 part += __shfl_xor(part, 16); part += __shfl_xor(part, 32);
;                 if (fq == 0) ssq[(size_t)row * 16 + u.pn * 4 + wc] = part; }
	v_lshlrev_b32_e32 v214, 16, v168
	v_and_b32_e32 v215, 0xffff0000, v168
	v_lshlrev_b32_e32 v216, 16, v169
	v_and_b32_e32 v217, 0xffff0000, v169
	v_add_f32_e32 v44, v44, v214
	v_add_f32_e32 v45, v45, v215
	v_add_f32_e32 v46, v46, v216
	v_add_f32_e32 v47, v47, v217
	v_mul_f32_e32 v218, v45, v45
	v_mul_f32_e32 v219, v47, v47
	v_fmac_f32_e32 v218, v44, v44
	v_fmac_f32_e32 v219, v46, v46
	v_add_f32_e32 v220, v218, v219
	v_lshlrev_b32_e32 v214, 16, v170
	v_and_b32_e32 v215, 0xffff0000, v170
	v_lshlrev_b32_e32 v216, 16, v171
	v_and_b32_e32 v217, 0xffff0000, v171
	v_add_f32_e32 v40, v40, v214
	v_add_f32_e32 v41, v41, v215
	v_add_f32_e32 v42, v42, v216
	v_add_f32_e32 v43, v43, v217
	v_mul_f32_e32 v218, v41, v41
	v_mul_f32_e32 v219, v43, v43
	v_fmac_f32_e32 v218, v40, v40
	v_fmac_f32_e32 v219, v42, v42
	v_add_f32_e32 v221, v218, v219
	v_cvt_pk_bf16_f32 v44, v44, v45
	v_cvt_pk_bf16_f32 v45, v46, v47
	v_cvt_pk_bf16_f32 v46, v40, v41
	v_cvt_pk_bf16_f32 v47, v42, v43
	v_add_u32_e32 v230, 0x48000, v226
	global_store_dwordx4 v230, v[44:47], s[6:7]
	v_lshlrev_b32_e32 v214, 16, v172
	v_and_b32_e32 v215, 0xffff0000, v172
	v_lshlrev_b32_e32 v216, 16, v173
	v_and_b32_e32 v217, 0xffff0000, v173
	v_add_f32_e32 v36, v36, v214
	v_add_f32_e32 v37, v37, v215
	v_add_f32_e32 v38, v38, v216
	v_add_f32_e32 v39, v39, v217
	v_mul_f32_e32 v218, v37, v37
	v_mul_f32_e32 v219, v39, v39
	v_fmac_f32_e32 v218, v36, v36
	v_fmac_f32_e32 v219, v38, v38
	v_add_f32_e32 v222, v218, v219
	v_lshlrev_b32_e32 v214, 16, v174
	v_and_b32_e32 v215, 0xffff0000, v174
	v_lshlrev_b32_e32 v216, 16, v175
	v_and_b32_e32 v217, 0xffff0000, v175
	v_add_f32_e32 v32, v32, v214
	v_add_f32_e32 v33, v33, v215
	v_add_f32_e32 v34, v34, v216
	v_add_f32_e32 v35, v35, v217
	v_mul_f32_e32 v218, v33, v33
	v_mul_f32_e32 v219, v35, v35
	v_fmac_f32_e32 v218, v32, v32
	v_fmac_f32_e32 v219, v34, v34
	v_add_f32_e32 v223, v218, v219
	v_cvt_pk_bf16_f32 v36, v36, v37
	v_cvt_pk_bf16_f32 v37, v38, v39
	v_cvt_pk_bf16_f32 v38, v32, v33
	v_cvt_pk_bf16_f32 v39, v34, v35
	global_store_dwordx4 v230, v[36:39], s[6:7] offset:256
	v_add_f32_e32 v220, v220, v221
	v_add_f32_e32 v222, v222, v223
	v_add_f32_e32 v224, v220, v222
	v_add_u32_e32 v231, 0x2400, v227
	v_mov_b32_e32 v225, v224
	s_nop 1
	v_permlane16_swap_b32_e32 v224, v225
	v_add_f32_e32 v224, v224, v225
	v_mov_b32_e32 v225, v224
	s_nop 1
	v_permlane32_swap_b32_e32 v224, v225
	v_add_f32_e32 v224, v224, v225
	s_and_saveexec_b64 s[0:1], vcc
	global_store_dword v231, v224, s[8:9]
	s_or_b64 exec, exec, s[0:1]
	s_waitcnt vmcnt(20)
	v_lshlrev_b32_e32 v214, 16, v176
	v_and_b32_e32 v215, 0xffff0000, v176
	v_lshlrev_b32_e32 v216, 16, v177
	v_and_b32_e32 v217, 0xffff0000, v177
	v_add_f32_e32 v28, v28, v214
	v_add_f32_e32 v29, v29, v215
	v_add_f32_e32 v30, v30, v216
	v_add_f32_e32 v31, v31, v217
	v_mul_f32_e32 v218, v29, v29
	v_mul_f32_e32 v219, v31, v31
	v_fmac_f32_e32 v218, v28, v28
	v_fmac_f32_e32 v219, v30, v30
	v_add_f32_e32 v220, v218, v219
	v_lshlrev_b32_e32 v214, 16, v178
	v_and_b32_e32 v215, 0xffff0000, v178
	v_lshlrev_b32_e32 v216, 16, v179
	v_and_b32_e32 v217, 0xffff0000, v179
	v_add_f32_e32 v24, v24, v214
	v_add_f32_e32 v25, v25, v215
	v_add_f32_e32 v26, v26, v216
	v_add_f32_e32 v27, v27, v217
	v_mul_f32_e32 v218, v25, v25
	v_mul_f32_e32 v219, v27, v27
	v_fmac_f32_e32 v218, v24, v24
	v_fmac_f32_e32 v219, v26, v26
	v_add_f32_e32 v221, v218, v219
	v_cvt_pk_bf16_f32 v28, v28, v29
	v_cvt_pk_bf16_f32 v29, v30, v31
	v_cvt_pk_bf16_f32 v30, v24, v25
	v_cvt_pk_bf16_f32 v31, v26, v27
	v_add_u32_e32 v230, 0x50000, v226
	global_store_dwordx4 v230, v[28:31], s[6:7]
	v_lshlrev_b32_e32 v214, 16, v180
	v_and_b32_e32 v215, 0xffff0000, v180
	v_lshlrev_b32_e32 v216, 16, v181
	v_and_b32_e32 v217, 0xffff0000, v181
	v_add_f32_e32 v20, v20, v214
	v_add_f32_e32 v21, v21, v215
	v_add_f32_e32 v22, v22, v216
	v_add_f32_e32 v23, v23, v217
	v_mul_f32_e32 v218, v21, v21
	v_mul_f32_e32 v219, v23, v23
	v_fmac_f32_e32 v218, v20, v20
	v_fmac_f32_e32 v219, v22, v22
	v_add_f32_e32 v222, v218, v219
	v_lshlrev_b32_e32 v214, 16, v182
	v_and_b32_e32 v215, 0xffff0000, v182
	v_lshlrev_b32_e32 v216, 16, v183
	v_and_b32_e32 v217, 0xffff0000, v183
	v_add_f32_e32 v16, v16, v214
	v_add_f32_e32 v17, v17, v215
	v_add_f32_e32 v18, v18, v216
	v_add_f32_e32 v19, v19, v217
	v_mul_f32_e32 v218, v17, v17
	v_mul_f32_e32 v219, v19, v19
	v_fmac_f32_e32 v218, v16, v16
	v_fmac_f32_e32 v219, v18, v18
	v_add_f32_e32 v223, v218, v219
	v_cvt_pk_bf16_f32 v20, v20, v21
	v_cvt_pk_bf16_f32 v21, v22, v23
	v_cvt_pk_bf16_f32 v22, v16, v17
	v_cvt_pk_bf16_f32 v23, v18, v19
	global_store_dwordx4 v230, v[20:23], s[6:7] offset:256
	v_add_f32_e32 v220, v220, v221
	v_add_f32_e32 v222, v222, v223
	v_add_f32_e32 v224, v220, v222
	v_add_u32_e32 v231, 0x2800, v227
	v_mov_b32_e32 v225, v224
	s_nop 1
	v_permlane16_swap_b32_e32 v224, v225
	v_add_f32_e32 v224, v224, v225
	v_mov_b32_e32 v225, v224
	s_nop 1
	v_permlane32_swap_b32_e32 v224, v225
	v_add_f32_e32 v224, v224, v225
	s_and_saveexec_b64 s[0:1], vcc
	global_store_dword v231, v224, s[8:9]
	s_or_b64 exec, exec, s[0:1]
	s_waitcnt vmcnt(21)
; __device__ __forceinline__ u32x4 pack8(const f32x4 v0, const f32x4 v1) { u32x4 w; w.x = cvt_pk_bf16(v0[0], v0[1]); w.y = cvt_pk_bf16(v0[2], v0[3]); w.z = cvt_pk_bf16(v1[0], v1[1]); w.w = cvt_pk_bf16(v1[2], v1[3]); return w; }
; __device__ __forceinline__ float sumsq8(const f32x4 a, const f32x4 b) { return ((a[0] * a[0] + a[1] * a[1]) + (a[2] * a[2] + a[3] * a[3])) + ((b[0] * b[0] + b[1] * b[1]) + (b[2] * b[2] + b[3] * b[3])); }
; __device__ __forceinline__ void unpack8(const u32x4 w, f32x4& a, f32x4& b) { a = (f32x4){bf_lo(w.x), bf_hi(w.x), bf_lo(w.y), bf_hi(w.y)}; b = (f32x4){bf_lo(w.z), bf_hi(w.z), bf_lo(w.w), bf_hi(w.w)}; }
; #define PG8_BAR __builtin_amdgcn_s_barrier()
;     __device__ __forceinline__ void operator()(const f32x4 (&acc)[2][2][4][2], const Unit& u, int wr, int wc, int fr, int fq) const {
;     ...
; #pragma unroll
;         for (int ai = 0; ai < 2; ++ai)
; #pragma unroll
;             for (int m = 0; m < 4; ++m) { const int row = row0 + ai * HALF + m * 16; float part = 0.f;
; #pragma unroll
;                 for (int bj = 0; bj < 2; ++bj) { f32x4 r0, r1; unpack8(rv[ai * 4 + m][bj], r0, r1);
;                     const f32x4 h0 = r0 + acc[ai][bj][m][0], h1 = r1 + acc[ai][bj][m][1]; part += sumsq8(h0, h1);
;                     *(u32x4*)(XBo + (size_t)row * DMODEL + col0 + bj * HALF) = pack8(h0, h1); }
;                 part += __shfl_xor(part, 16); part += __shfl_xor(part, 32);
;                 if (fq == 0) ssq[(size_t)row * 16 + u.pn * 4 + wc] = part; }
; template <class Epi, class Sched, bool ALIGN_EPI = false, bool SP2 = false>
; __device__ __forceinline__ void gemm_phase(PG8_LAS unsigned char* lds, const Gemm g, const Sched& S, const Epi& E) {
;     ...
;         if (!has_next) break;
; #pragma unroll
;         for (int a = 0; a < 2; ++a)
; #pragma unroll
;             for (int b = 0; b < 2; ++b)
; #pragma unroll
;                 for (int m = 0; m < 4; ++m)
; #pragma unroll
;                     for (int n = 0; n < 2; ++n) acc[a][b][m][n] = (f32x4){0.f, 0.f, 0.f, 0.f};
;         cur = nxt; cA = nA; cB = nB; ++ui; relax = Epi::LOADS_BEFORE_STORES && !Epi::AFTER_DRAIN && SP2;
;         if constexpr (ALIGN_EPI) { if (wr == 1) PG8_BAR; }
	v_lshlrev_b32_e32 v214, 16, v184
	v_and_b32_e32 v215, 0xffff0000, v184
	v_lshlrev_b32_e32 v216, 16, v185
	v_and_b32_e32 v217, 0xffff0000, v185
	v_add_f32_e32 v12, v12, v214
	v_add_f32_e32 v13, v13, v215
	v_add_f32_e32 v14, v14, v216
	v_add_f32_e32 v15, v15, v217
	v_mul_f32_e32 v218, v13, v13
	v_mul_f32_e32 v219, v15, v15
	v_fmac_f32_e32 v218, v12, v12
	v_fmac_f32_e32 v219, v14, v14
	v_add_f32_e32 v220, v218, v219
	v_lshlrev_b32_e32 v214, 16, v186
	v_and_b32_e32 v215, 0xffff0000, v186
	v_lshlrev_b32_e32 v216, 16, v187
	v_and_b32_e32 v217, 0xffff0000, v187
	v_add_f32_e32 v8, v8, v214
	v_add_f32_e32 v9, v9, v215
	v_add_f32_e32 v10, v10, v216
	v_add_f32_e32 v11, v11, v217
	v_mul_f32_e32 v218, v9, v9
	v_mul_f32_e32 v219, v11, v11
	v_fmac_f32_e32 v218, v8, v8
	v_fmac_f32_e32 v219, v10, v10
	v_add_f32_e32 v221, v218, v219
	v_cvt_pk_bf16_f32 v12, v12, v13
	v_cvt_pk_bf16_f32 v13, v14, v15
	v_cvt_pk_bf16_f32 v14, v8, v9
	v_cvt_pk_bf16_f32 v15, v10, v11
	v_add_u32_e32 v230, 0x58000, v226
	global_store_dwordx4 v230, v[12:15], s[6:7]
	v_lshlrev_b32_e32 v214, 16, v188
	v_and_b32_e32 v215, 0xffff0000, v188
	v_lshlrev_b32_e32 v216, 16, v189
	v_and_b32_e32 v217, 0xffff0000, v189
	v_add_f32_e32 v4, v4, v214
	v_add_f32_e32 v5, v5, v215
	v_add_f32_e32 v6, v6, v216
	v_add_f32_e32 v7, v7, v217
	v_mul_f32_e32 v218, v5, v5
	v_mul_f32_e32 v219, v7, v7
	v_fmac_f32_e32 v218, v4, v4
	v_fmac_f32_e32 v219, v6, v6
	v_add_f32_e32 v222, v218, v219
	v_lshlrev_b32_e32 v214, 16, v190
	v_and_b32_e32 v215, 0xffff0000, v190
	v_lshlrev_b32_e32 v216, 16, v191
	v_and_b32_e32 v217, 0xffff0000, v191
	v_add_f32_e32 v0, v0, v214
	v_add_f32_e32 v1, v1, v215
	v_add_f32_e32 v2, v2, v216
	v_add_f32_e32 v3, v3, v217
	v_mul_f32_e32 v218, v1, v1
	v_mul_f32_e32 v219, v3, v3
	v_fmac_f32_e32 v218, v0, v0
	v_fmac_f32_e32 v219, v2, v2
	v_add_f32_e32 v223, v218, v219
	v_cvt_pk_bf16_f32 v4, v4, v5
	v_cvt_pk_bf16_f32 v5, v6, v7
	v_cvt_pk_bf16_f32 v6, v0, v1
	v_cvt_pk_bf16_f32 v7, v2, v3
	global_store_dwordx4 v230, v[4:7], s[6:7] offset:256
	v_add_f32_e32 v220, v220, v221
	v_add_f32_e32 v222, v222, v223
	v_add_f32_e32 v224, v220, v222
	v_add_u32_e32 v231, 0x2c00, v227
	v_mov_b32_e32 v225, v224
	s_nop 1
	v_permlane16_swap_b32_e32 v224, v225
	v_add_f32_e32 v224, v224, v225
	v_mov_b32_e32 v225, v224
	s_nop 1
	v_permlane32_swap_b32_e32 v224, v225
	v_add_f32_e32 v224, v224, v225
	s_and_saveexec_b64 s[0:1], vcc
	global_store_dword v231, v224, s[8:9]
	s_or_b64 exec, exec, s[0:1]
	s_mov_b64 s[26:27], -1
	s_andn2_b64 vcc, exec, s[16:17]
	s_mov_b64 s[0:1], -1
	s_cbranch_vccnz .LBB0_955
	s_andn2_b64 vcc, exec, s[4:5]
	s_cbranch_vccnz .LBB0_954
	s_barrier
	s_branch .LBB0_954
